# grid barrier spin loops poll back-to-back (s_sleep removed from the arrival-counter polls)
# baseline (speedup 1.0000x reference)
; DI unsigned xb_ld(unsigned* p) { return __hip_atomic_load(p, __ATOMIC_RELAXED, __HIP_MEMORY_SCOPE_AGENT); }
; #define XB_SPIN(cond, bar) do { unsigned _sp = 0; while (cond) { __builtin_amdgcn_s_sleep(1); \
;     if ((++_sp & 255u) == 0u) { if (xb_ld(&(bar)[XB_TMO])) break; if (_sp > XB_SPIN_CAP) { atomicAdd(&(bar)[XB_TMO], 1u); break; } } } } while (0)
; DI void xcd_barrier(const XcdBarrier& b) {
;     ...
;       else XB_SPIN(xb_ld(&bar[XB_TOPGEN]) == tg, bar);
.LBB0_76:
	s_and_b32 s14, s3, 0xff
	s_mov_b64 s[12:13], -1
	s_cmp_lg_u32 s14, 0
	s_mov_b64 s[16:17], -1
	s_nop 0
	s_cbranch_scc0 .LBB0_79
	s_and_b64 vcc, exec, s[16:17]
	s_cbranch_vccz .LBB0_75

; DI unsigned xb_ld(unsigned* p) { return __hip_atomic_load(p, __ATOMIC_RELAXED, __HIP_MEMORY_SCOPE_AGENT); }
; #define XB_SPIN(cond, bar) do { unsigned _sp = 0; while (cond) { __builtin_amdgcn_s_sleep(1); \
;     if ((++_sp & 255u) == 0u) { if (xb_ld(&(bar)[XB_TMO])) break; if (_sp > XB_SPIN_CAP) { atomicAdd(&(bar)[XB_TMO], 1u); break; } } } } while (0)
; DI void xcd_barrier(const XcdBarrier& b) {
;     ...
;       else XB_SPIN(xb_ld(&bar[XB_TOPGEN]) == tg, bar);
.LBB0_93:
	s_and_b32 s12, s3, 0xff
	s_cmp_lg_u32 s12, 0
	s_mov_b64 s[14:15], -1
	s_nop 0
	s_cbranch_scc0 .LBB0_96
	s_mov_b64 s[16:17], -1
	s_and_b64 vcc, exec, s[14:15]
	s_cbranch_vccz .LBB0_92

; DI unsigned xb_ld(unsigned* p) { return __hip_atomic_load(p, __ATOMIC_RELAXED, __HIP_MEMORY_SCOPE_AGENT); }
; #define XB_SPIN(cond, bar) do { unsigned _sp = 0; while (cond) { __builtin_amdgcn_s_sleep(1); \
;     if ((++_sp & 255u) == 0u) { if (xb_ld(&(bar)[XB_TMO])) break; if (_sp > XB_SPIN_CAP) { atomicAdd(&(bar)[XB_TMO], 1u); break; } } } } while (0)
; DI void xcd_barrier(const XcdBarrier& b) {
;     ...
;       else XB_SPIN(xb_ld(&bar[XB_TOPGEN]) == tg, bar);
.LBB0_163:
	s_and_b32 s20, s38, 0xff
	s_mov_b64 s[18:19], -1
	s_cmp_lg_u32 s20, 0
	s_mov_b64 s[36:37], -1
	s_nop 0
	s_cbranch_scc0 .LBB0_166
	s_and_b64 vcc, exec, s[36:37]
	s_cbranch_vccz .LBB0_162

; DI unsigned xb_ld(unsigned* p) { return __hip_atomic_load(p, __ATOMIC_RELAXED, __HIP_MEMORY_SCOPE_AGENT); }
; #define XB_SPIN(cond, bar) do { unsigned _sp = 0; while (cond) { __builtin_amdgcn_s_sleep(1); \
;     if ((++_sp & 255u) == 0u) { if (xb_ld(&(bar)[XB_TMO])) break; if (_sp > XB_SPIN_CAP) { atomicAdd(&(bar)[XB_TMO], 1u); break; } } } } while (0)
; DI void xcd_barrier(const XcdBarrier& b) {
;     ...
;       else XB_SPIN(xb_ld(&bar[XB_TOPGEN]) == tg, bar);
.LBB0_362:
	s_and_b32 s36, s40, 0xff
	s_mov_b64 s[18:19], -1
	s_cmp_lg_u32 s36, 0
	s_mov_b64 s[38:39], -1
	s_nop 0
	s_cbranch_scc0 .LBB0_365
	s_and_b64 vcc, exec, s[38:39]
	s_cbranch_vccz .LBB0_361

; DI unsigned xb_ld(unsigned* p) { return __hip_atomic_load(p, __ATOMIC_RELAXED, __HIP_MEMORY_SCOPE_AGENT); }
; #define XB_SPIN(cond, bar) do { unsigned _sp = 0; while (cond) { __builtin_amdgcn_s_sleep(1); \
;     if ((++_sp & 255u) == 0u) { if (xb_ld(&(bar)[XB_TMO])) break; if (_sp > XB_SPIN_CAP) { atomicAdd(&(bar)[XB_TMO], 1u); break; } } } } while (0)
; DI void xcd_barrier(const XcdBarrier& b) {
;     ...
;       else XB_SPIN(xb_ld(&bar[XB_TOPGEN]) == tg, bar);
.LBB0_493:
	s_and_b32 s34, s38, 0xff
	s_mov_b64 s[18:19], -1
	s_cmp_lg_u32 s34, 0
	s_mov_b64 s[36:37], -1
	s_nop 0
	s_cbranch_scc0 .LBB0_496
	s_and_b64 vcc, exec, s[36:37]
	s_cbranch_vccz .LBB0_492
